# transposed b64 stores in SSD and mLSTM conv blocks: half the lanes write the odd channel row first so each 16-lane group covers all bank classes
# baseline (speedup 1.0000x reference)
.LBB0_404:
	s_or_b64 exec, exec, s[56:57]
	s_and_b64 s[30:31], s[40:41], exec
	s_mov_b32 s9, 0xab34000
	s_cselect_b32 s9, s9, 0xed34000
	v_readlane_b32 s30, v254, 53
	s_add_u32 s29, s30, s9
	v_min_i32_e32 v0, 0xbf, v69
	s_movk_i32 s9, 0xffbf
	v_add_u32_e32 v0, 64, v0
	v_cmp_lt_i32_e32 vcc, s9, v69
	v_min_i32_e32 v4, 0xbf, v70
	v_add_u32_e32 v4, 64, v4
	v_cndmask_b32_e32 v0, 0, v0, vcc
	v_cmp_lt_i32_e32 vcc, s9, v70
	v_cndmask_b32_e64 v78, 64, -1, s[44:45]
	v_sub_u32_e32 v1, 0xff, v0
	v_cndmask_b32_e32 v4, 0, v4, vcc
	v_sub_u32_e32 v5, 0xff, v4
	v_add_u32_e32 v8, 64, v78
	v_sub_u32_e32 v9, 0xbf, v78
	v_add_u32_e32 v14, 64, v71
	v_sub_u32_e32 v15, 0xbf, v71
	v_cndmask_b32_e64 v0, v1, v0, s[40:41]
	v_cndmask_b32_e64 v4, v5, v4, s[40:41]
	v_cndmask_b32_e64 v8, v9, v8, s[40:41]
	v_cndmask_b32_e64 v14, v15, v14, s[40:41]
	v_or_b32_e32 v20, 64, v62
	v_xor_b32_e32 v21, 0xbf, v62
	v_add_u32_e32 v0, s16, v0
	v_mov_b64_e32 v[12:13], s[12:13]
	v_add_u32_e32 v4, s16, v4
	v_add_u32_e32 v8, s16, v8
	v_add_u32_e32 v14, s16, v14
	v_cndmask_b32_e64 v20, v21, v20, s[40:41]
	v_mad_i64_i32 v[0:1], s[34:35], v0, s20, v[12:13]
	v_mad_i64_i32 v[4:5], s[34:35], v4, s20, v[12:13]
	v_mul_lo_u32 v8, v8, s20
	v_mov_b32_e32 v9, v169
	v_mad_i64_i32 v[12:13], s[34:35], v14, s20, v[12:13]
	v_or_b32_e32 v20, s16, v20
	v_mov_b32_e32 v19, v169
	v_lshl_add_u64 v[8:9], s[12:13], 0, v[8:9]
	v_lshl_add_u64 v[12:13], v[12:13], 0, s[84:85]
	v_mul_lo_u32 v20, v20, s21
	v_mov_b32_e32 v21, v169
	v_lshl_add_u64 v[0:1], v[0:1], 0, v[18:19]
	v_lshl_add_u64 v[4:5], v[4:5], 0, v[18:19]
	v_lshl_add_u64 v[8:9], v[8:9], 0, v[18:19]
	v_lshl_add_u64 v[12:13], v[12:13], 0, v[168:169]
	v_lshl_add_u64 v[20:21], s[14:15], 0, v[20:21]
	s_mov_b32 s9, s85
	v_lshl_add_u64 v[0:1], v[0:1], 0, s[84:85]
	v_lshl_add_u64 v[4:5], v[4:5], 0, s[84:85]
	v_lshl_add_u64 v[8:9], v[8:9], 0, s[84:85]
	v_add_co_u32_e32 v12, vcc, s38, v12
	v_lshl_add_u64 v[20:21], v[20:21], 0, s[8:9]
	s_mov_b32 s77, s85
	v_ashrrev_i32_e32 v31, 6, v16
	v_lshl_add_u64 v[0:1], v[0:1], 0, v[168:169]
	v_lshl_add_u64 v[4:5], v[4:5], 0, v[168:169]
	v_lshl_add_u64 v[8:9], v[8:9], 0, v[168:169]
	v_addc_co_u32_e32 v13, vcc, 0, v13, vcc
	v_lshl_add_u64 v[20:21], v[20:21], 0, s[76:77]
	s_movk_i32 s9, 0x880
	v_lshlrev_b32_e32 v80, 1, v62
	global_load_dwordx4 v[0:3], v[0:1], off offset:3664
	v_mul_lo_u32 v79, v31, s9
	global_load_dwordx4 v[4:7], v[4:5], off offset:3664
	s_movk_i32 s9, 0x480
	global_load_dwordx4 v[8:11], v[8:9], off offset:3664
	s_movk_i32 s34, 0x90
	global_load_dwordx4 v[12:15], v[12:13], off offset:592
	s_nop 0
	global_load_dword v82, v[20:21], off offset:256
	global_load_dword v83, v[20:21], off offset:272
	v_add_u32_e32 v20, 0, v80
	v_add_u32_e32 v22, v20, v79
	s_waitcnt lgkmcnt(0)
	s_barrier
	ds_read_u16 v21, v22 offset:59904
	ds_read_u16 v23, v22 offset:60176
	ds_read_u16 v24, v22 offset:60448
	v_mov_b32_e32 v51, v50
	v_mov_b32_e32 v49, v48
	s_waitcnt lgkmcnt(2)
	v_lshlrev_b32_e32 v21, 16, v21
	s_waitcnt lgkmcnt(1)
	v_lshlrev_b32_e32 v23, 16, v23
	v_mul_f32_e32 v25, v64, v23
	s_waitcnt lgkmcnt(0)
	v_lshlrev_b32_e32 v24, 16, v24
	v_fmac_f32_e32 v25, v63, v21
	v_fmac_f32_e32 v25, v65, v24
	v_add_f32_e32 v21, v66, v25
	v_mul_f32_e32 v25, 0xbfb8aa3b, v21
	v_exp_f32_e32 v25, v25
	v_mul_f32_e32 v26, v64, v24
	v_fmac_f32_e32 v26, v63, v23
	v_mov_b32_e32 v53, v52
	v_add_f32_e32 v25, 1.0, v25
	v_rcp_f32_e32 v25, v25
	v_mov_b32_e32 v55, v54
	v_readlane_b32 s31, v254, 54
	s_addc_u32 s30, s31, 0
	v_mul_f32_e32 v21, v21, v25
	v_mul_lo_u32 v25, v31, s9
	v_cvt_pk_bf16_f32 v21, v21, s0
	v_add_u32_e32 v81, v20, v25
	ds_write_b16 v81, v21
	v_lshl_or_b32 v21, v31, 3, 1
	v_mul_lo_u32 v84, v21, s36
	v_add_u32_e32 v32, v20, v84
	ds_read_u16 v25, v32 offset:60448
	v_mul_lo_u32 v21, v21, s34
	v_add_u32_e32 v85, v20, v21
	ds_read_u16 v20, v32 offset:60720
	s_add_i32 s9, 0, 0x13720
	s_waitcnt lgkmcnt(1)
	v_lshlrev_b32_e32 v25, 16, v25
	v_fmac_f32_e32 v26, v65, v25
	v_add_f32_e32 v23, v66, v26
	v_mul_f32_e32 v26, 0xbfb8aa3b, v23
	v_exp_f32_e32 v26, v26
	v_mul_f32_e32 v21, v64, v25
	s_waitcnt lgkmcnt(0)
	v_lshlrev_b32_e32 v20, 16, v20
	v_fmac_f32_e32 v21, v63, v24
	v_add_f32_e32 v26, 1.0, v26
	v_rcp_f32_e32 v26, v26
	v_fmac_f32_e32 v21, v65, v20
	v_add_f32_e32 v21, v66, v21
	v_lshl_add_u32 v92, v31, 5, s9
	v_mul_f32_e32 v23, v23, v26
	v_cvt_pk_bf16_f32 v23, v23, s0
	ds_write_b16 v85, v23
	v_mul_f32_e32 v23, 0xbfb8aa3b, v21
	v_exp_f32_e32 v23, v23
	s_add_i32 s31, 0, 0x13020
	v_and_b32_e32 v28, 1, v31
	v_lshrrev_b32_e32 v30, 4, v62
	v_add_f32_e32 v23, 1.0, v23
	v_rcp_f32_e32 v23, v23
	v_lshlrev_b32_e32 v29, 5, v28
	v_and_b32_e32 v95, 48, v16
	v_cmp_gt_u32_e32 vcc, 16, v16
	v_mul_f32_e32 v21, v21, v23
	v_cvt_pk_bf16_f32 v21, v21, s0
	ds_write_b16 v85, v21 offset:144
	ds_read_u16 v21, v32 offset:60992
	v_mul_f32_e32 v23, v64, v20
	v_fmac_f32_e32 v23, v63, v25
	v_mov_b32_e32 v16, 0x4510
	s_lshl_b32 s28, s28, 13
	s_waitcnt lgkmcnt(0)
	v_lshlrev_b32_e32 v21, 16, v21
	v_fmac_f32_e32 v23, v65, v21
	v_add_f32_e32 v23, v66, v23
	v_mul_f32_e32 v24, 0xbfb8aa3b, v23
	v_exp_f32_e32 v24, v24
	v_cndmask_b32_e64 v106, v16, 0, vcc
	v_lshlrev_b32_e32 v16, 3, v30
	v_mul_u32_u24_e32 v103, 0x90, v17
	v_add_f32_e32 v24, 1.0, v24
	v_rcp_f32_e32 v24, v24
	v_mad_u32_u24 v104, v17, s34, 0
	v_cmp_eq_u32_e64 s[50:51], 0, v17
	v_cmp_lt_u32_e64 s[52:53], 1, v17
	v_mul_f32_e32 v23, v23, v24
	v_cvt_pk_bf16_f32 v23, v23, s0
	ds_write_b16 v85, v23 offset:288
	ds_read_u16 v23, v32 offset:61264
	v_mul_f32_e32 v24, v64, v21
	v_fmac_f32_e32 v24, v63, v20
	v_cmp_lt_u32_e64 s[54:55], 3, v17
	v_cmp_lt_u32_e64 s[56:57], 7, v17
	s_waitcnt lgkmcnt(0)
	v_lshlrev_b32_e32 v23, 16, v23
	v_fmac_f32_e32 v24, v65, v23
	v_add_f32_e32 v20, v66, v24
	v_mul_f32_e32 v24, 0xbfb8aa3b, v20
	v_exp_f32_e32 v24, v24
	v_lshl_add_u64 v[18:19], s[12:13], 0, v[18:19]
	v_lshl_add_u64 v[18:19], v[18:19], 0, s[84:85]
	v_lshl_add_u64 v[56:57], v[18:19], 0, v[168:169]
	v_add_f32_e32 v24, 1.0, v24
	v_rcp_f32_e32 v24, v24
	v_lshlrev_b32_e32 v18, 6, v28
	v_mov_b32_e32 v19, v169
	s_mov_b32 s17, 0
	v_mul_f32_e32 v20, v20, v24
	v_cvt_pk_bf16_f32 v20, v20, s0
	ds_write_b16 v85, v20 offset:432
	ds_read_u16 v20, v32 offset:61536
	v_mul_f32_e32 v24, v64, v23
	v_fmac_f32_e32 v24, v63, v21
	v_cmp_eq_u32_e64 s[48:49], 0, v28
	v_add_u32_e32 v86, 0x110, v84
	s_waitcnt lgkmcnt(0)
	v_lshlrev_b32_e32 v20, 16, v20
	v_fmac_f32_e32 v24, v65, v20
	v_add_f32_e32 v21, v66, v24
	v_mul_f32_e32 v24, 0xbfb8aa3b, v21
	v_exp_f32_e32 v24, v24
	v_add_u32_e32 v87, 0x220, v84
	v_add_u32_e32 v88, 0x330, v84
	v_add_u32_e32 v89, 0x440, v84
	v_add_f32_e32 v24, 1.0, v24
	v_rcp_f32_e32 v24, v24
	v_add_u32_e32 v90, 0x550, v84
	v_add_u32_e32 v91, 0x660, v84
	v_add_u32_e32 v97, 0, v95
	v_mul_f32_e32 v21, v21, v24
	v_cvt_pk_bf16_f32 v21, v21, s0
	ds_write_b16 v85, v21 offset:576
	ds_read_u16 v21, v32 offset:61808
	v_mul_f32_e32 v24, v64, v20
	v_fmac_f32_e32 v24, v63, v23
	v_cndmask_b32_e64 v105, 64, -1, vcc
	v_cmp_lt_u32_e64 s[58:59], 31, v62
	s_waitcnt lgkmcnt(0)
	v_lshlrev_b32_e32 v21, 16, v21
	v_fmac_f32_e32 v24, v65, v21
	v_add_f32_e32 v23, v66, v24
	v_mul_f32_e32 v24, 0xbfb8aa3b, v23
	v_exp_f32_e32 v24, v24
	v_mul_f32_e32 v21, v64, v21
	v_fmac_f32_e32 v21, v63, v20
	v_mov_b32_e32 v115, 0
	v_add_f32_e32 v24, 1.0, v24
	v_rcp_f32_e32 v24, v24
	s_nop 0
	v_mul_f32_e32 v23, v23, v24
	v_cvt_pk_bf16_f32 v23, v23, s0
	ds_write_b16 v85, v23 offset:720
	ds_read_u16 v23, v32 offset:62080
	s_waitcnt lgkmcnt(0)
	v_lshlrev_b32_e32 v23, 16, v23
	v_fmac_f32_e32 v21, v65, v23
	v_add_f32_e32 v20, v66, v21
	v_mul_f32_e32 v21, 0xbfb8aa3b, v20
	v_exp_f32_e32 v21, v21
	s_nop 0
	v_add_f32_e32 v21, 1.0, v21
	v_rcp_f32_e32 v21, v21
	s_nop 0
	v_mul_f32_e32 v20, v20, v21
	v_cvt_pk_bf16_f32 v20, v20, s0
	ds_write_b16 v85, v20 offset:864
	ds_read_u16 v20, v32 offset:61392
	ds_read_u16 v21, v32 offset:61664
	ds_read_u16 v23, v32 offset:61936
	ds_read_u16 v24, v32 offset:62208
	ds_read_u16 v26, v32 offset:60848
	ds_read_u16 v27, v32 offset:61120
	ds_read_u16 v33, v22 offset:60576
	ds_read_u16 v32, v32 offset:60576
	s_waitcnt lgkmcnt(7)
	v_lshlrev_b32_e32 v20, 16, v20
	s_waitcnt lgkmcnt(6)
	v_lshlrev_b32_e32 v21, 16, v21
	s_waitcnt lgkmcnt(3)
	v_lshlrev_b32_e32 v26, 16, v26
	s_waitcnt lgkmcnt(1)
	v_lshlrev_b32_e32 v36, 16, v33
	s_waitcnt lgkmcnt(0)
	v_lshlrev_b32_e32 v37, 16, v32
	ds_read_u16 v32, v22 offset:60032
	ds_read_u16 v22, v22 offset:60304
	v_lshlrev_b32_e32 v27, 16, v27
	v_lshlrev_b32_e32 v25, 16, v23
	v_lshlrev_b32_e32 v23, 16, v24
	s_waitcnt lgkmcnt(1)
	v_lshlrev_b32_e32 v38, 16, v32
	s_waitcnt lgkmcnt(0)
	v_lshlrev_b32_e32 v39, 16, v22
	v_pk_mov_b32 v[40:41], v[38:39], v[36:37] op_sel:[1,0]
	ds_read_b128 v[32:35], v92
	v_pk_mul_f32 v[40:41], v[50:51], v[40:41] op_sel_hi:[0,1]
	v_pk_fma_f32 v[38:39], v[48:49], v[38:39], v[40:41] op_sel_hi:[0,1,1]
	v_pk_fma_f32 v[38:39], v[52:53], v[36:37], v[38:39] op_sel_hi:[0,1,1]
	v_pk_add_f32 v[38:39], v[54:55], v[38:39] op_sel_hi:[0,1]
	v_mul_f32_e32 v22, 0xbfb8aa3b, v38
	v_exp_f32_e32 v22, v22
	v_mov_b32_e32 v24, v21
	v_add_f32_e32 v22, 1.0, v22
	v_rcp_f32_e32 v40, v22
	v_mul_f32_e32 v22, 0xbfb8aa3b, v39
	v_exp_f32_e32 v22, v22
	s_nop 0
	v_add_f32_e32 v22, 1.0, v22
	v_rcp_f32_e32 v41, v22
	s_nop 0
	v_pk_mul_f32 v[38:39], v[38:39], v[40:41]
	s_nop 0
	v_pk_mul_f32 v[38:39], v[38:39], s[92:93] op_sel_hi:[1,0]
	v_pk_mov_b32 v[40:41], v[26:27], v[20:21] op_sel:[1,0]
	v_cvt_pk_bf16_f32 v22, v38, s0
	ds_write_b16 v81, v22 offset:9216
	v_cvt_pk_bf16_f32 v22, v39, s0
	s_waitcnt lgkmcnt(1)
	v_pk_mul_f32 v[38:39], v[32:33], v[38:39]
	v_pk_mov_b32 v[32:33], v[36:37], v[26:27] op_sel:[1,0]
	ds_write_b16 v85, v22 offset:9216
	v_pk_mul_f32 v[32:33], v[50:51], v[32:33] op_sel_hi:[0,1]
	v_pk_fma_f32 v[32:33], v[48:49], v[36:37], v[32:33] op_sel_hi:[0,1,1]
	v_pk_fma_f32 v[32:33], v[52:53], v[26:27], v[32:33] op_sel_hi:[0,1,1]
	v_pk_add_f32 v[32:33], v[54:55], v[32:33] op_sel_hi:[0,1]
	v_mul_f32_e32 v22, 0xbfb8aa3b, v32
	v_exp_f32_e32 v22, v22
	v_pk_mul_f32 v[40:41], v[50:51], v[40:41] op_sel_hi:[0,1]
	v_pk_fma_f32 v[26:27], v[48:49], v[26:27], v[40:41] op_sel_hi:[0,1,1]
	v_pk_fma_f32 v[26:27], v[52:53], v[20:21], v[26:27] op_sel_hi:[0,1,1]
	v_add_f32_e32 v22, 1.0, v22
	v_rcp_f32_e32 v36, v22
	v_mul_f32_e32 v22, 0xbfb8aa3b, v33
	v_exp_f32_e32 v22, v22
	v_pk_add_f32 v[26:27], v[54:55], v[26:27] op_sel_hi:[0,1]
	v_add_f32_e32 v22, 1.0, v22
	v_rcp_f32_e32 v37, v22
	s_nop 0
	v_pk_mul_f32 v[32:33], v[32:33], v[36:37]
	s_nop 0
	v_pk_mul_f32 v[32:33], v[32:33], s[92:93] op_sel_hi:[1,0]
	s_nop 0
	v_cvt_pk_bf16_f32 v22, v32, s0
	ds_write_b16 v85, v22 offset:9360
	v_cvt_pk_bf16_f32 v22, v33, s0
	ds_write_b16 v85, v22 offset:9504
	v_mul_f32_e32 v22, 0xbfb8aa3b, v26
	v_exp_f32_e32 v22, v22
	v_pk_mul_f32 v[36:37], v[34:35], v[32:33]
	ds_read_b128 v[32:35], v92 offset:16
	v_add_f32_e32 v22, 1.0, v22
	v_rcp_f32_e32 v40, v22
	v_mul_f32_e32 v22, 0xbfb8aa3b, v27
	v_exp_f32_e32 v22, v22
	s_nop 0
	v_add_f32_e32 v22, 1.0, v22
	v_rcp_f32_e32 v41, v22
	s_nop 0
	v_pk_mul_f32 v[26:27], v[26:27], v[40:41]
	s_nop 0
	v_pk_mul_f32 v[26:27], v[26:27], s[92:93] op_sel_hi:[1,0]
	s_nop 0
	v_cvt_pk_bf16_f32 v22, v26, s0
	ds_write_b16 v85, v22 offset:9648
	v_cvt_pk_bf16_f32 v22, v27, s0
	ds_write_b16 v85, v22 offset:9792
	v_mov_b32_e32 v22, v25
	v_pk_mul_f32 v[24:25], v[50:51], v[24:25] op_sel_hi:[0,1]
	v_pk_fma_f32 v[20:21], v[48:49], v[20:21], v[24:25] op_sel_hi:[0,1,1]
	v_pk_fma_f32 v[20:21], v[52:53], v[22:23], v[20:21] op_sel_hi:[0,1,1]
	v_pk_add_f32 v[20:21], v[54:55], v[20:21] op_sel_hi:[0,1]
	v_mul_f32_e32 v22, 0xbfb8aa3b, v20
	v_mul_f32_e32 v23, 0xbfb8aa3b, v21
	v_exp_f32_e32 v22, v22
	v_exp_f32_e32 v23, v23
	s_waitcnt lgkmcnt(2)
	v_pk_mul_f32 v[26:27], v[32:33], v[26:27]
	v_lshlrev_b32_e32 v32, 8, v30
	v_add_f32_e32 v22, 1.0, v22
	v_add_f32_e32 v23, 1.0, v23
	v_rcp_f32_e32 v22, v22
	v_rcp_f32_e32 v23, v23
	v_add_u32_e32 v33, v104, v16
	v_pk_mul_f32 v[20:21], v[20:21], v[22:23]
	s_nop 0
	v_pk_mul_f32 v[20:21], v[20:21], s[92:93] op_sel_hi:[1,0]
	s_nop 0
	v_cvt_pk_bf16_f32 v22, v20, s0
	v_pk_mul_f32 v[24:25], v[34:35], v[20:21]
	ds_write_b16 v85, v22 offset:9936
	v_cvt_pk_bf16_f32 v22, v21, s0
	v_cvt_pk_bf16_f32 v23, v24, v25
	v_mul_u32_u24_e32 v24, 0x90, v62
	v_lshlrev_b32_e32 v25, 4, v31
	ds_write_b16 v85, v22 offset:10080
	v_cvt_pk_bf16_f32 v20, v38, v39
	v_cvt_pk_bf16_f32 v21, v36, v37
	v_cvt_pk_bf16_f32 v22, v26, v27
	v_add3_u32 v93, 0, v24, v25
	ds_write_b128 v93, v[20:23] offset:18432
	v_and_b32_e32 v20, -16, v71
	v_or_b32_e32 v94, v20, v17
	v_lshlrev_b32_e32 v22, 2, v62
	v_mul_lo_u32 v21, v94, s34
	v_add_u32_e32 v98, s31, v22
	s_add_i32 s31, 0, 0x13120
	v_add_u32_e32 v31, 0, v21
	v_lshlrev_b32_e32 v21, 2, v30
	v_add_u32_e32 v99, s31, v22
	s_add_i32 s31, 0, 0x13220
	v_add_u32_e32 v101, s9, v22
	v_readlane_b32 s9, v253, 45
	v_lshlrev_b32_e32 v30, 1, v20
	v_or_b32_e32 v20, v29, v17
	v_or_b32_e32 v109, v29, v21
	s_add_u32 s8, s14, s8
	v_lshl_add_u32 v102, v94, 2, s9
	v_mul_u32_u24_e32 v108, 0x90, v20
	v_or_b32_e32 v20, 3, v109
	s_addc_u32 s9, s15, 0
	v_cmp_gt_i32_e64 s[64:65], v20, v94
	v_or_b32_e32 v20, 16, v29
	s_add_u32 s8, s8, s76
	v_or_b32_e32 v17, v20, v17
	s_addc_u32 s9, s9, 0
	v_mul_u32_u24_e32 v110, 0x90, v17
	v_or_b32_e32 v17, v20, v21
	s_add_u32 s34, s29, s84
	v_cmp_gt_i32_e64 s[68:69], v17, v94
	v_cmp_lt_i32_e64 s[70:71], v17, v94
	v_or_b32_e32 v20, 3, v17
	v_or_b32_e32 v21, 2, v17
	v_lshlrev_b32_e32 v29, 1, v17
	s_addc_u32 s35, s30, 0
	v_mov_b32_e32 v17, v169
	v_add_u32_e32 v100, s31, v22
	v_add3_u32 v107, 0, v16, v30
	v_or_b32_e32 v22, 2, v109
	v_lshlrev_b32_e32 v34, 1, v109
	v_lshl_add_u64 v[16:17], s[34:35], 0, v[16:17]
	v_add_u32_e32 v96, v31, v95
	v_cmp_gt_i32_e64 s[60:61], v109, v94
	v_cmp_lt_i32_e64 s[62:63], v109, v94
	v_cmp_gt_i32_e64 s[66:67], v22, v94
	v_cmp_gt_i32_e64 s[72:73], v20, v94
	v_cmp_gt_i32_e64 s[74:75], v21, v94
	v_lshl_add_u64 v[58:59], v[16:17], 0, v[18:19]
	v_mov_b32_e32 v24, 0
	v_mov_b32_e32 v25, 0
	v_mov_b32_e32 v26, 0
	v_mov_b32_e32 v27, 0
	v_mov_b32_e32 v16, 0
	v_mov_b32_e32 v17, 0
	v_mov_b32_e32 v18, 0
	v_mov_b32_e32 v19, 0
	v_mov_b32_e32 v20, 0
	v_mov_b32_e32 v21, 0
	v_mov_b32_e32 v22, 0
	v_mov_b32_e32 v23, 0
	v_add_u32_e32 v111, v31, v34
	v_add_u32_e32 v112, v31, v29
	v_add_u32_e32 v113, v102, v32
	v_add_u32_e32 v114, v33, v30
	s_mov_b32 s29, 0
	s_waitcnt lgkmcnt(0)
	s_barrier
	v_lshrrev_b32_e32 v196, 6, v171
	v_lshlrev_b32_e32 v196, 1, v196
	v_bfe_u32 v197, v171, 3, 1
	v_add_u32_e32 v196, v196, v197
	v_lshlrev_b32_e32 v196, 2, v196
	v_bfe_u32 v197, v171, 4, 2
	v_lshlrev_b32_e32 v197, 3, v197
	v_and_b32_e32 v202, 7, v171
	v_add_u32_e32 v197, v197, v202
	v_mul_u32_u24_e32 v198, 0x110, v196
	v_lshl_add_u32 v198, v197, 2, v198
	v_add_u32_e32 v198, 0xea00, v198
	v_mul_u32_u24_e32 v199, 0x90, v196
	v_lshl_add_u32 v199, v197, 2, v199
	v_mul_u32_u24_e32 v200, 0x120, v197
	v_lshl_add_u32 v200, v196, 1, v200
	v_lshlrev_b32_e32 v201, 2, v196
	v_add_u32_e32 v201, 0x13720, v201
	v_lshlrev_b32_e32 v202, 3, v197
	v_add_u32_e32 v203, 4, v202
	ds_bpermute_b32 v172, v202, v63
	ds_bpermute_b32 v173, v203, v63
	ds_bpermute_b32 v174, v202, v64
	ds_bpermute_b32 v175, v203, v64
	ds_bpermute_b32 v176, v202, v65
	ds_bpermute_b32 v177, v203, v65
	ds_bpermute_b32 v178, v202, v66
	ds_bpermute_b32 v179, v203, v66
	ds_bpermute_b32 v180, v202, v48
	ds_bpermute_b32 v181, v203, v48
	ds_bpermute_b32 v182, v202, v50
	ds_bpermute_b32 v183, v203, v50
	ds_bpermute_b32 v184, v202, v52
	ds_bpermute_b32 v185, v203, v52
	ds_bpermute_b32 v186, v202, v54
	ds_bpermute_b32 v187, v203, v54
	v_bfe_u32 v250, v171, 2, 1
	v_mul_u32_u24_e32 v250, 0x90, v250
	s_waitcnt lgkmcnt(0)
	v_and_b32_e32 v240, 7, v171
	v_lshrrev_b32_e32 v239, 3, v171
	v_lshlrev_b32_e32 v239, 1, v239
	v_add_u32_e32 v222, 0, v240
	v_and_b32_e32 v222, 7, v222
	v_lshl_add_u32 v222, v240, 3, v222
	v_mul_u32_u24_e32 v222, 0x90, v222
	v_add_u32_e32 v222, v222, v239
	v_add_u32_e32 v223, 1, v240
	v_and_b32_e32 v223, 7, v223
	v_lshl_add_u32 v223, v240, 3, v223
	v_mul_u32_u24_e32 v223, 0x90, v223
	v_add_u32_e32 v223, v223, v239
	v_add_u32_e32 v224, 2, v240
	v_and_b32_e32 v224, 7, v224
	v_lshl_add_u32 v224, v240, 3, v224
	v_mul_u32_u24_e32 v224, 0x90, v224
	v_add_u32_e32 v224, v224, v239
	v_add_u32_e32 v225, 3, v240
	v_and_b32_e32 v225, 7, v225
	v_lshl_add_u32 v225, v240, 3, v225
	v_mul_u32_u24_e32 v225, 0x90, v225
	v_add_u32_e32 v225, v225, v239
	v_add_u32_e32 v226, 4, v240
	v_and_b32_e32 v226, 7, v226
	v_lshl_add_u32 v226, v240, 3, v226
	v_mul_u32_u24_e32 v226, 0x90, v226
	v_add_u32_e32 v226, v226, v239
	v_add_u32_e32 v227, 5, v240
	v_and_b32_e32 v227, 7, v227
	v_lshl_add_u32 v227, v240, 3, v227
	v_mul_u32_u24_e32 v227, 0x90, v227
	v_add_u32_e32 v227, v227, v239
	v_add_u32_e32 v228, 6, v240
	v_and_b32_e32 v228, 7, v228
	v_lshl_add_u32 v228, v240, 3, v228
	v_mul_u32_u24_e32 v228, 0x90, v228
	v_add_u32_e32 v228, v228, v239
	v_add_u32_e32 v229, 7, v240
	v_and_b32_e32 v229, 7, v229
	v_lshl_add_u32 v229, v240, 3, v229
	v_mul_u32_u24_e32 v229, 0x90, v229
	v_add_u32_e32 v229, v229, v239
	v_and_b32_e32 v230, 1, v171
	v_lshlrev_b32_e32 v230, 4, v230
	s_branch .LBB0_406
.LBB0_405:
	s_or_b64 exec, exec, s[76:77]
	v_mov_b32_e32 v31, s31
	ds_read_b32 v31, v31 offset:252
	s_add_i32 s17, s17, 64
	s_mul_i32 s35, s78, 0x7b80
	s_mul_i32 s29, s78, 0x7c00
	s_mul_i32 s78, s78, 0x16c20
	v_add_u32_e32 v122, s35, v198
	v_add_u32_e32 v124, s29, v201
	v_add_u32_e32 v123, s78, v200
	v_mov_b32_e32 v154, 0xbfb8aa3b
	ds_read_b32 v131, v122 offset:128
	ds_read_b32 v133, v122 offset:400
	ds_read_b32 v135, v122 offset:672
	ds_read_b32 v137, v122 offset:944
	ds_read_b32 v139, v122 offset:1216
	ds_read_b32 v141, v122 offset:1488
	ds_read_b128 v[156:159], v124
	s_waitcnt lgkmcnt(5)
	v_add_f32_e32 v115, v30, v31
	v_lshlrev_b32_e32 v130, 16, v131
	v_and_b32_e32 v131, 0xffff0000, v131
	v_lshlrev_b32_e32 v132, 16, v133
	v_and_b32_e32 v133, 0xffff0000, v133
	s_waitcnt lgkmcnt(2)
	v_lshlrev_b32_e32 v134, 16, v135
	v_and_b32_e32 v135, 0xffff0000, v135
	v_lshlrev_b32_e32 v136, 16, v137
	v_and_b32_e32 v137, 0xffff0000, v137
	v_lshlrev_b32_e32 v138, 16, v139
	v_and_b32_e32 v139, 0xffff0000, v139
	s_waitcnt lgkmcnt(1)
	v_lshlrev_b32_e32 v140, 16, v141
	v_and_b32_e32 v141, 0xffff0000, v141
	v_pk_mul_f32 v[160:161], v[180:181], v[130:131]
	v_pk_mul_f32 v[162:163], v[180:181], v[132:133]
	v_pk_mul_f32 v[164:165], v[180:181], v[134:135]
	v_pk_mul_f32 v[166:167], v[180:181], v[136:137]
	v_pk_fma_f32 v[160:161], v[182:183], v[132:133], v[160:161]
	v_pk_fma_f32 v[162:163], v[182:183], v[134:135], v[162:163]
	v_pk_fma_f32 v[164:165], v[182:183], v[136:137], v[164:165]
	v_pk_fma_f32 v[166:167], v[182:183], v[138:139], v[166:167]
	v_pk_fma_f32 v[160:161], v[184:185], v[134:135], v[160:161]
	v_pk_fma_f32 v[162:163], v[184:185], v[136:137], v[162:163]
	v_pk_fma_f32 v[164:165], v[184:185], v[138:139], v[164:165]
	v_pk_fma_f32 v[166:167], v[184:185], v[140:141], v[166:167]
	v_pk_add_f32 v[160:161], v[186:187], v[160:161]
	v_pk_add_f32 v[162:163], v[186:187], v[162:163]
	v_pk_add_f32 v[164:165], v[186:187], v[164:165]
	v_pk_add_f32 v[166:167], v[186:187], v[166:167]
	v_pk_mul_f32 v[188:189], v[160:161], v[154:155] op_sel_hi:[1,0]
	v_pk_mul_f32 v[190:191], v[162:163], v[154:155] op_sel_hi:[1,0]
	v_pk_mul_f32 v[192:193], v[164:165], v[154:155] op_sel_hi:[1,0]
	v_pk_mul_f32 v[194:195], v[166:167], v[154:155] op_sel_hi:[1,0]
	v_exp_f32_e32 v188, v188
	v_exp_f32_e32 v190, v190
	v_exp_f32_e32 v192, v192
	v_exp_f32_e32 v194, v194
	v_exp_f32_e32 v189, v189
	v_exp_f32_e32 v191, v191
	v_exp_f32_e32 v193, v193
	v_exp_f32_e32 v195, v195
	v_pk_add_f32 v[188:189], v[188:189], 1.0 op_sel_hi:[1,0]
	v_pk_add_f32 v[190:191], v[190:191], 1.0 op_sel_hi:[1,0]
	v_pk_add_f32 v[192:193], v[192:193], 1.0 op_sel_hi:[1,0]
	v_pk_add_f32 v[194:195], v[194:195], 1.0 op_sel_hi:[1,0]
	v_rcp_f32_e32 v188, v188
	v_rcp_f32_e32 v190, v190
	v_rcp_f32_e32 v192, v192
	v_rcp_f32_e32 v194, v194
	v_rcp_f32_e32 v189, v189
	v_rcp_f32_e32 v191, v191
	v_rcp_f32_e32 v193, v193
	v_rcp_f32_e32 v195, v195
	v_pk_mul_f32 v[160:161], v[160:161], v[188:189]
	v_pk_mul_f32 v[162:163], v[162:163], v[190:191]
	v_pk_mul_f32 v[164:165], v[164:165], v[192:193]
	v_pk_mul_f32 v[166:167], v[166:167], v[194:195]
	v_pk_mul_f32 v[160:161], v[160:161], s[92:93] op_sel_hi:[1,0]
	v_pk_mul_f32 v[162:163], v[162:163], s[92:93] op_sel_hi:[1,0]
	v_pk_mul_f32 v[164:165], v[164:165], s[92:93] op_sel_hi:[1,0]
	v_pk_mul_f32 v[166:167], v[166:167], s[92:93] op_sel_hi:[1,0]
	v_cvt_pk_bf16_f32 v188, v160, v161
	v_cvt_pk_bf16_f32 v190, v162, v163
	v_cvt_pk_bf16_f32 v192, v164, v165
	v_cvt_pk_bf16_f32 v194, v166, v167
	ds_write_b32 v199, v188 offset:9216
	ds_write_b32 v199, v190 offset:9360
	ds_write_b32 v199, v192 offset:9504
	ds_write_b32 v199, v194 offset:9648
	s_waitcnt lgkmcnt(4)
	v_pk_mul_f32 v[196:197], v[160:161], v[156:157] op_sel_hi:[1,0]
	v_pk_mul_f32 v[202:203], v[162:163], v[156:157] op_sel:[0,1]
	v_pk_mul_f32 v[204:205], v[164:165], v[158:159] op_sel_hi:[1,0]
	v_pk_mul_f32 v[206:207], v[166:167], v[158:159] op_sel:[0,1]
	v_cvt_pk_bf16_f32 v188, v196, v202
	v_cvt_pk_bf16_f32 v189, v204, v206
	v_cvt_pk_bf16_f32 v190, v197, v203
	v_cvt_pk_bf16_f32 v191, v205, v207
	v_and_b32_e32 v192, 4, v171
	v_cmp_ne_u32_e32 vcc, 0, v192
	v_add_u32_e32 v248, v123, v250
	v_sub_u32_e32 v249, v123, v250
	v_cndmask_b32_e32 v192, v188, v190, vcc
	v_cndmask_b32_e32 v193, v189, v191, vcc
	v_cndmask_b32_e32 v194, v190, v188, vcc
	v_cndmask_b32_e32 v195, v191, v189, vcc
	ds_write_b64 v248, v[192:193] offset:18432
	ds_write_b64 v249, v[194:195] offset:18576
	s_cmpk_eq_i32 s34, 0x84
	s_mov_b32 s29, s34
	s_waitcnt lgkmcnt(0)
	s_barrier
	s_cbranch_scc1 .LBB0_420

.LBB0_441:
	s_or_b64 exec, exec, s[52:53]
	v_cndmask_b32_e64 v81, 64, -1, s[46:47]
	v_add_u32_e32 v13, 64, v81
	v_sub_u32_e32 v14, 0xbf, v81
	v_cndmask_b32_e64 v13, v14, v13, s[40:41]
	v_add_u32_e32 v13, s28, v13
	v_mul_lo_u32 v14, v13, s20
	v_mov_b32_e32 v15, v169
	v_lshl_add_u64 v[14:15], s[12:13], 0, v[14:15]
	v_mov_b32_e32 v13, v169
	v_lshl_add_u64 v[12:13], v[12:13], 1, v[14:15]
	v_or_b32_e32 v14, 64, v62
	v_xor_b32_e32 v15, 0xbf, v62
	v_cndmask_b32_e64 v14, v15, v14, s[40:41]
	v_or_b32_e32 v14, s28, v14
	s_and_b64 s[16:17], s[40:41], exec
	s_mov_b32 s9, 0xab34000
	v_mul_lo_u32 v14, v14, s21
	v_mov_b32_e32 v15, v169
	s_cselect_b32 s9, s9, 0xed34000
	v_readlane_b32 s16, v254, 53
	v_lshl_add_u64 v[14:15], s[14:15], 0, v[14:15]
	s_add_u32 s16, s16, s9
	v_mov_b32_e32 v57, v169
	v_lshl_add_u64 v[14:15], v[14:15], 0, s[84:85]
	s_mov_b32 s9, s85
	v_ashrrev_i32_e32 v37, 6, v17
	v_lshl_add_u64 v[12:13], v[12:13], 0, v[56:57]
	v_lshl_add_u64 v[18:19], v[14:15], 0, s[8:9]
	global_load_dwordx4 v[12:15], v[12:13], off
	s_nop 0
	global_load_dword v88, v[18:19], off offset:128
	v_lshlrev_b32_e32 v83, 1, v62
	v_lshl_or_b32 v18, v37, 3, 1
	s_movk_i32 s9, 0xc80
	v_add_u32_e32 v16, 0, v83
	v_mul_lo_u32 v86, v18, s29
	s_movk_i32 s35, 0x90
	v_mul_lo_u32 v82, v37, s9
	s_movk_i32 s9, 0x480
	v_add_u32_e32 v61, v16, v86
	v_mul_lo_u32 v97, v18, s35
	v_mul_lo_u32 v95, v37, s9
	v_add_u32_e32 v100, 0x90, v97
	v_add_u32_e32 v102, 0x120, v97
	v_add_u32_e32 v101, 0x4b0, v61
	v_add_u32_e32 v104, 0x1b0, v97
	v_add_u32_e32 v107, 0x240, v97
	v_add_u32_e32 v108, 0x2d0, v97
	v_add_u32_e32 v109, 0x360, v97
	s_waitcnt lgkmcnt(0)
	s_barrier
	v_add_u32_e32 v39, v16, v82
	v_add_u32_e32 v84, v16, v95
	v_add_u32_e32 v87, v16, v97
	v_add_u32_e32 v98, 0x190, v61
	v_add_u32_e32 v89, v16, v100
	v_add_u32_e32 v99, 0x320, v61
	v_add_u32_e32 v90, v16, v102
	v_add_u32_e32 v94, v16, v104
	v_add_u32_e32 v103, 0x640, v61
	v_add_u32_e32 v114, v16, v107
	v_add_u32_e32 v105, 0x7d0, v61
	v_add_u32_e32 v91, v16, v108
	v_add_u32_e32 v106, 0x960, v61
	v_add_u32_e32 v96, v16, v109
	ds_read_u16 v16, v101 offset:65440
	ds_read_u16 v18, v103 offset:65440
	ds_read_u16 v92, v105 offset:65440
	ds_read_u16 v19, v106 offset:65440
	ds_read_u16 v112, v99 offset:65440
	s_waitcnt lgkmcnt(4)
	v_lshlrev_b32_e32 v54, 16, v16
	ds_read_u16 v115, v98 offset:65440
	ds_read_u16 v16, v61 offset:65440
	ds_read_u16 v20, v39 offset:65440
	ds_read_u16 v41, v39 offset:64640
	s_waitcnt vmcnt(5)
	ds_read_u16 v21, v39 offset:65040
	v_mov_b32_e32 v45, v44
	s_waitcnt lgkmcnt(3)
	v_lshlrev_b32_e32 v51, 16, v16
	s_waitcnt lgkmcnt(2)
	v_lshlrev_b32_e32 v50, 16, v20
	s_waitcnt lgkmcnt(1)
	v_lshlrev_b32_e32 v48, 16, v41
	s_waitcnt lgkmcnt(0)
	v_lshlrev_b32_e32 v49, 16, v21
	v_mov_b32_e32 v16, v43
	v_pk_mov_b32 v[52:53], v[48:49], v[50:51] op_sel:[1,0]
	v_mov_b32_e32 v41, v40
	v_pk_mul_f32 v[52:53], v[16:17], v[52:53] op_sel_hi:[0,1]
	v_pk_fma_f32 v[48:49], v[40:41], v[48:49], v[52:53] op_sel_hi:[0,1,1]
	v_pk_fma_f32 v[48:49], v[42:43], v[50:51], v[48:49] op_sel_hi:[0,1,1]
	v_pk_add_f32 v[48:49], v[44:45], v[48:49] op_sel_hi:[0,1]
	v_mul_f32_e32 v52, 0xbfb8aa3b, v48
	v_mul_f32_e32 v53, 0xbfb8aa3b, v49
	v_exp_f32_e32 v52, v52
	v_exp_f32_e32 v53, v53
	v_lshlrev_b32_e32 v113, 16, v112
	v_lshlrev_b32_e32 v112, 16, v115
	v_add_f32_e32 v52, 1.0, v52
	v_add_f32_e32 v53, 1.0, v53
	v_rcp_f32_e32 v52, v52
	v_rcp_f32_e32 v53, v53
	v_lshlrev_b32_e32 v55, 16, v18
	v_lshlrev_b32_e32 v111, 16, v92
	v_mov_b32_e32 v110, v55
	v_pk_mul_f32 v[48:49], v[48:49], v[52:53]
	v_pk_mov_b32 v[52:53], v[50:51], v[112:113] op_sel:[1,0]
	v_cvt_pk_bf16_f32 v92, v48, s0
	v_pk_mul_f32 v[52:53], v[16:17], v[52:53] op_sel_hi:[0,1]
	v_pk_fma_f32 v[50:51], v[40:41], v[50:51], v[52:53] op_sel_hi:[0,1,1]
	v_pk_fma_f32 v[50:51], v[42:43], v[112:113], v[50:51] op_sel_hi:[0,1,1]
	v_pk_add_f32 v[50:51], v[44:45], v[50:51] op_sel_hi:[0,1]
	v_mul_f32_e32 v52, 0xbfb8aa3b, v50
	v_mul_f32_e32 v53, 0xbfb8aa3b, v51
	v_exp_f32_e32 v52, v52
	v_exp_f32_e32 v53, v53
	ds_write_b16 v84, v92 offset:9216
	v_cvt_pk_bf16_f32 v92, v49, s0
	v_add_f32_e32 v52, 1.0, v52
	v_add_f32_e32 v53, 1.0, v53
	v_rcp_f32_e32 v52, v52
	v_rcp_f32_e32 v53, v53
	ds_write_b16 v87, v92 offset:9216
	v_lshlrev_b32_e32 v93, 16, v19
	v_readlane_b32 s17, v254, 54
	v_pk_mul_f32 v[50:51], v[50:51], v[52:53]
	v_pk_mov_b32 v[52:53], v[112:113], v[54:55] op_sel:[1,0]
	v_cvt_pk_bf16_f32 v115, v50, s0
	v_pk_mul_f32 v[52:53], v[16:17], v[52:53] op_sel_hi:[0,1]
	v_pk_fma_f32 v[52:53], v[40:41], v[112:113], v[52:53] op_sel_hi:[0,1,1]
	v_pk_fma_f32 v[52:53], v[42:43], v[54:55], v[52:53] op_sel_hi:[0,1,1]
	v_pk_add_f32 v[52:53], v[44:45], v[52:53] op_sel_hi:[0,1]
	v_mul_f32_e32 v92, 0xbfb8aa3b, v52
	v_exp_f32_e32 v92, v92
	v_mul_f32_e32 v112, 0xbfb8aa3b, v53
	v_exp_f32_e32 v113, v112
	ds_write_b16 v89, v115 offset:9216
	v_add_f32_e32 v92, 1.0, v92
	v_rcp_f32_e32 v112, v92
	v_add_f32_e32 v92, 1.0, v113
	v_rcp_f32_e32 v113, v92
	v_cvt_pk_bf16_f32 v92, v51, s0
	ds_write_b16 v90, v92 offset:9216
	v_mov_b32_e32 v92, v111
	v_pk_mul_f32 v[110:111], v[16:17], v[110:111] op_sel_hi:[0,1]
	v_pk_fma_f32 v[54:55], v[40:41], v[54:55], v[110:111] op_sel_hi:[0,1,1]
	v_pk_fma_f32 v[54:55], v[42:43], v[92:93], v[54:55] op_sel_hi:[0,1,1]
	v_pk_add_f32 v[54:55], v[44:45], v[54:55] op_sel_hi:[0,1]
	v_mul_f32_e32 v16, 0xbfb8aa3b, v54
	v_exp_f32_e32 v16, v16
	v_mul_f32_e32 v92, 0xbfb8aa3b, v55
	v_exp_f32_e32 v93, v92
	v_pk_mul_f32 v[52:53], v[52:53], v[112:113]
	v_add_f32_e32 v16, 1.0, v16
	v_rcp_f32_e32 v92, v16
	v_add_f32_e32 v16, 1.0, v93
	v_rcp_f32_e32 v93, v16
	v_cvt_pk_bf16_f32 v110, v52, s0
	v_cvt_pk_bf16_f32 v16, v53, s0
	ds_write_b16 v94, v110 offset:9216
	v_pk_mul_f32 v[54:55], v[54:55], v[92:93]
	ds_write_b16 v114, v16 offset:9216
	v_cvt_pk_bf16_f32 v16, v54, s0
	v_lshlrev_b32_e32 v35, 5, v37
	s_addc_u32 s17, s17, 0
	s_add_i32 s9, 0, 0x16520
	ds_write_b16 v91, v16 offset:9216
	v_cvt_pk_bf16_f32 v16, v55, s0
	v_add_u32_e32 v46, 0xfc00, v39
	v_add_u32_e32 v85, s9, v35
	ds_write_b16 v96, v16 offset:9216
	ds_read_b128 v[18:21], v85
	ds_read_u16 v16, v39 offset:65168
	ds_read_u16 v46, v46 offset:1056
	ds_read_u16 v92, v39 offset:64768
	v_add_u32_e32 v110, 0x10020, v61
	v_add_u32_e32 v111, 0x101b0, v61
	s_waitcnt lgkmcnt(2)
	v_lshlrev_b32_e32 v16, 16, v16
	s_waitcnt lgkmcnt(1)
	v_lshlrev_b32_e32 v46, 16, v46
	s_waitcnt lgkmcnt(0)
	v_lshlrev_b32_e32 v92, 16, v92
	v_mul_f32_e32 v92, v63, v92
	v_fmac_f32_e32 v92, v64, v16
	v_fmac_f32_e32 v92, v65, v46
	v_add_f32_e32 v92, v66, v92
	v_mul_f32_e32 v93, 0xbfb8aa3b, v92
	v_exp_f32_e32 v93, v93
	v_add_u32_e32 v112, 0x10340, v61
	v_add_u32_e32 v113, 0x104d0, v61
	v_add_u32_e32 v115, 0x10660, v61
	v_add_f32_e32 v93, 1.0, v93
	v_rcp_f32_e32 v93, v93
	ds_read_u16 v110, v110
	ds_read_u16 v111, v111
	ds_read_u16 v112, v112
	ds_read_u16 v113, v113
	ds_read_u16 v115, v115
	v_mul_f32_e32 v16, v63, v16
	s_waitcnt lgkmcnt(4)
	v_lshlrev_b32_e32 v110, 16, v110
	v_fmac_f32_e32 v16, v64, v46
	v_fmac_f32_e32 v16, v65, v110
	v_add_f32_e32 v16, v66, v16
	v_mul_f32_e32 v92, v92, v93
	v_mul_f32_e32 v116, 0xbfb8aa3b, v16
	v_cvt_pk_bf16_f32 v92, v92, s0
	v_mul_f32_e32 v93, v64, v110
	v_exp_f32_e32 v116, v116
	ds_write_b16 v84, v92
	s_waitcnt lgkmcnt(4)
	v_lshlrev_b32_e32 v92, 16, v111
	v_fmac_f32_e32 v93, v63, v46
	v_fmac_f32_e32 v93, v65, v92
	v_add_f32_e32 v46, v66, v93
	s_waitcnt lgkmcnt(3)
	v_lshlrev_b32_e32 v111, 16, v112
	v_mul_f32_e32 v112, v64, v92
	v_mul_f32_e32 v93, 0xbfb8aa3b, v46
	v_fmac_f32_e32 v112, v63, v110
	v_add_f32_e32 v116, 1.0, v116
	v_exp_f32_e32 v93, v93
	v_fmac_f32_e32 v112, v65, v111
	v_rcp_f32_e32 v116, v116
	v_add_f32_e32 v110, v66, v112
	v_mul_f32_e32 v112, 0xbfb8aa3b, v110
	v_exp_f32_e32 v112, v112
	v_add_f32_e32 v93, 1.0, v93
	v_mul_f32_e32 v16, v16, v116
	v_rcp_f32_e32 v93, v93
	v_cvt_pk_bf16_f32 v16, v16, s0
	ds_write_b16 v87, v16
	v_add_f32_e32 v16, 1.0, v112
	v_rcp_f32_e32 v16, v16
	v_mul_f32_e32 v46, v46, v93
	v_cvt_pk_bf16_f32 v46, v46, s0
	ds_write_b16 v89, v46
	s_waitcnt lgkmcnt(4)
	v_lshlrev_b32_e32 v46, 16, v113
	v_mul_f32_e32 v16, v110, v16
	v_mul_f32_e32 v89, v64, v111
	v_mul_f32_e32 v110, v64, v46
	v_fmac_f32_e32 v89, v63, v92
	s_waitcnt lgkmcnt(3)
	v_lshlrev_b32_e32 v93, 16, v115
	v_fmac_f32_e32 v110, v63, v111
	v_fmac_f32_e32 v89, v65, v46
	v_fmac_f32_e32 v110, v65, v93
	v_add_f32_e32 v89, v66, v89
	v_add_f32_e32 v110, v66, v110
	v_mul_f32_e32 v92, 0xbfb8aa3b, v89
	v_mul_f32_e32 v111, 0xbfb8aa3b, v110
	v_exp_f32_e32 v92, v92
	v_exp_f32_e32 v111, v111
	v_cvt_pk_bf16_f32 v16, v16, s0
	ds_write_b16 v90, v16
	v_add_f32_e32 v92, 1.0, v92
	v_add_f32_e32 v16, 1.0, v111
	v_rcp_f32_e32 v92, v92
	v_rcp_f32_e32 v16, v16
	v_pk_mul_f32 v[18:19], v[18:19], v[48:49]
	v_pk_mul_f32 v[20:21], v[20:21], v[50:51]
	v_mul_f32_e32 v89, v89, v92
	v_mul_f32_e32 v16, v110, v16
	v_cvt_pk_bf16_f32 v89, v89, s0
	v_cvt_pk_bf16_f32 v16, v16, s0
	ds_write_b16 v94, v89
	ds_write_b16 v114, v16
	v_add_u32_e32 v16, 0x107f0, v61
	ds_read_u16 v16, v16
	v_or_b32_e32 v114, 16, v35
	v_add_u32_e32 v89, s9, v114
	ds_read_b128 v[110:113], v89
	v_cvt_pk_bf16_f32 v18, v18, v19
	s_waitcnt lgkmcnt(1)
	v_lshlrev_b32_e32 v94, 16, v16
	v_mul_f32_e32 v16, v64, v93
	v_fmac_f32_e32 v16, v63, v46
	v_fmac_f32_e32 v16, v65, v94
	v_add_f32_e32 v92, v66, v16
	v_mul_f32_e32 v16, 0xbfb8aa3b, v92
	v_exp_f32_e32 v46, v16
	v_mul_f32_e32 v94, v64, v94
	v_fmac_f32_e32 v94, v63, v93
	s_waitcnt lgkmcnt(0)
	v_pk_mul_f32 v[50:51], v[112:113], v[54:55]
	v_add_f32_e32 v46, 1.0, v46
	v_rcp_f32_e32 v117, v46
	v_cndmask_b32_e64 v46, 0, v33, s[40:41]
	v_cvt_pk_bf16_f32 v19, v20, v21
	v_cvt_pk_bf16_f32 v21, v50, v51
	v_mul_f32_e32 v33, v92, v117
	v_cvt_pk_bf16_f32 v33, v33, s0
	ds_write_b16 v91, v33
	v_add_u32_e32 v33, 0x10980, v61
	ds_read_u16 v33, v33
	s_movk_i32 s34, 0xff72
	v_and_b32_e32 v115, 32, v35
	v_lshrrev_b32_e32 v116, 4, v62
	v_cmp_gt_u32_e64 s[46:47], 47, v59
	s_waitcnt lgkmcnt(0)
	v_lshlrev_b32_e32 v33, 16, v33
	v_fmac_f32_e32 v94, v65, v33
	v_add_f32_e32 v33, v66, v94
	v_mul_f32_e32 v93, 0xbfb8aa3b, v33
	v_exp_f32_e32 v117, v93
	s_lshl_b32 s30, s30, 13
	v_cmp_eq_u32_e64 s[74:75], 1, v47
	v_mov_b32_e32 v16, 0
	v_add_f32_e32 v48, 1.0, v117
	v_rcp_f32_e32 v117, v48
	v_pk_mul_f32 v[48:49], v[110:111], v[52:53]
	s_mov_b32 s29, 0
	v_cvt_pk_bf16_f32 v20, v48, v49
	v_mul_f32_e32 v33, v33, v117
	v_cvt_pk_bf16_f32 v33, v33, s0
	ds_write_b16 v96, v33
	v_mad_u32_u24 v33, v62, s35, 0
	v_lshl_add_u32 v49, v37, 4, v33
	ds_write_b128 v49, v[18:21] offset:27648
	v_mad_i32_i24 v18, v62, s34, v33
	v_add_u32_e32 v95, v18, v95
	s_add_i32 s34, 0, 0x16420
	v_add_u32_e32 v97, v18, v97
	v_add_u32_e32 v48, v18, v100
	v_add_u32_e32 v52, v18, v102
	v_add_u32_e32 v110, v18, v104
	v_add_u32_e32 v107, v18, v107
	v_add_u32_e32 v108, v18, v108
	v_add_u32_e32 v109, v18, v109
	ds_read_u16 v18, v101 offset:65312
	ds_read_u16 v19, v103 offset:65312
	ds_read_u16 v102, v105 offset:65312
	ds_read_u16 v20, v106 offset:65312
	ds_read_u16 v104, v99 offset:65312
	v_add_u32_e32 v96, s34, v35
	s_waitcnt lgkmcnt(4)
	v_lshlrev_b32_e32 v50, 16, v18
	ds_read_u16 v106, v98 offset:65312
	ds_read_u16 v18, v61 offset:65312
	ds_read_u16 v21, v39 offset:65312
	ds_read_u16 v33, v39 offset:64512
	ds_read_u16 v35, v39 offset:64912
	v_mov_b32_e32 v37, v36
	s_waitcnt lgkmcnt(3)
	v_lshlrev_b32_e32 v55, 16, v18
	s_waitcnt lgkmcnt(2)
	v_lshlrev_b32_e32 v54, 16, v21
	s_waitcnt lgkmcnt(1)
	v_lshlrev_b32_e32 v98, 16, v33
	s_waitcnt lgkmcnt(0)
	v_lshlrev_b32_e32 v99, 16, v35
	v_mov_b32_e32 v35, v34
	v_pk_mov_b32 v[100:101], v[98:99], v[54:55] op_sel:[1,0]
	v_mov_b32_e32 v33, v32
	v_pk_mul_f32 v[100:101], v[34:35], v[100:101] op_sel_hi:[0,1]
	v_pk_fma_f32 v[98:99], v[32:33], v[98:99], v[100:101] op_sel_hi:[0,1,1]
	v_pk_fma_f32 v[98:99], v[36:37], v[54:55], v[98:99] op_sel_hi:[0,1,1]
	v_mov_b32_e32 v39, v38
	v_pk_add_f32 v[98:99], v[38:39], v[98:99] op_sel_hi:[0,1]
	v_mul_f32_e32 v61, 0xbfb8aa3b, v98
	v_exp_f32_e32 v61, v61
	v_mul_f32_e32 v100, 0xbfb8aa3b, v99
	v_exp_f32_e32 v100, v100
	v_lshlrev_b32_e32 v101, 16, v102
	v_add_f32_e32 v61, 1.0, v61
	v_rcp_f32_e32 v102, v61
	v_add_f32_e32 v61, 1.0, v100
	v_rcp_f32_e32 v103, v61
	v_lshlrev_b32_e32 v105, 16, v104
	v_lshlrev_b32_e32 v104, 16, v106
	v_lshlrev_b32_e32 v51, 16, v19
	v_pk_mul_f32 v[98:99], v[98:99], v[102:103]
	v_pk_mov_b32 v[102:103], v[54:55], v[104:105] op_sel:[1,0]
	v_cvt_pk_bf16_f32 v61, v98, s0
	v_pk_mul_f32 v[102:103], v[34:35], v[102:103] op_sel_hi:[0,1]
	v_pk_fma_f32 v[54:55], v[32:33], v[54:55], v[102:103] op_sel_hi:[0,1,1]
	v_pk_fma_f32 v[54:55], v[36:37], v[104:105], v[54:55] op_sel_hi:[0,1,1]
	v_pk_add_f32 v[54:55], v[38:39], v[54:55] op_sel_hi:[0,1]
	v_mul_f32_e32 v102, 0xbfb8aa3b, v54
	v_exp_f32_e32 v102, v102
	v_mul_f32_e32 v103, 0xbfb8aa3b, v55
	v_exp_f32_e32 v103, v103
	ds_write_b16 v95, v61 offset:55296
	v_add_f32_e32 v61, 1.0, v102
	v_lshlrev_b32_e32 v53, 16, v20
	ds_read_b128 v[18:21], v96
	v_rcp_f32_e32 v102, v61
	v_add_f32_e32 v61, 1.0, v103
	v_rcp_f32_e32 v103, v61
	v_cvt_pk_bf16_f32 v61, v99, s0
	s_waitcnt lgkmcnt(0)
	v_pk_mul_f32 v[98:99], v[18:19], v[98:99]
	ds_write_b16 v97, v61 offset:55296
	v_pk_mul_f32 v[18:19], v[54:55], v[102:103]
	v_mov_b32_e32 v100, v51
	v_cvt_pk_bf16_f32 v54, v18, s0
	ds_write_b16 v48, v54 offset:55296
	v_pk_mov_b32 v[54:55], v[104:105], v[50:51] op_sel:[1,0]
	v_add_u32_e32 v111, s34, v114
	v_pk_mul_f32 v[54:55], v[34:35], v[54:55] op_sel_hi:[0,1]
	v_pk_fma_f32 v[54:55], v[32:33], v[104:105], v[54:55] op_sel_hi:[0,1,1]
	v_pk_fma_f32 v[54:55], v[36:37], v[50:51], v[54:55] op_sel_hi:[0,1,1]
	v_pk_add_f32 v[54:55], v[38:39], v[54:55] op_sel_hi:[0,1]
	v_mul_f32_e32 v48, 0xbfb8aa3b, v54
	v_exp_f32_e32 v48, v48
	v_mul_f32_e32 v61, 0xbfb8aa3b, v55
	v_exp_f32_e32 v61, v61
	v_cvt_pk_bf16_f32 v104, v19, s0
	ds_write_b16 v52, v104 offset:55296
	v_mov_b32_e32 v52, v101
	v_pk_mul_f32 v[100:101], v[34:35], v[100:101] op_sel_hi:[0,1]
	v_add_f32_e32 v48, 1.0, v48
	v_pk_fma_f32 v[50:51], v[32:33], v[50:51], v[100:101] op_sel_hi:[0,1,1]
	v_rcp_f32_e32 v102, v48
	v_add_f32_e32 v48, 1.0, v61
	v_pk_fma_f32 v[50:51], v[36:37], v[52:53], v[50:51] op_sel_hi:[0,1,1]
	v_rcp_f32_e32 v103, v48
	v_pk_add_f32 v[50:51], v[38:39], v[50:51] op_sel_hi:[0,1]
	v_mul_f32_e32 v52, 0xbfb8aa3b, v50
	v_exp_f32_e32 v52, v52
	v_mul_f32_e32 v53, 0xbfb8aa3b, v51
	v_exp_f32_e32 v53, v53
	v_pk_mul_f32 v[54:55], v[54:55], v[102:103]
	v_pk_mul_f32 v[104:105], v[20:21], v[18:19]
	v_cvt_pk_bf16_f32 v48, v54, s0
	ds_write_b16 v110, v48 offset:55296
	v_add_f32_e32 v48, 1.0, v52
	ds_read_b128 v[18:21], v111
	v_rcp_f32_e32 v52, v48
	v_add_f32_e32 v48, 1.0, v53
	v_rcp_f32_e32 v53, v48
	v_cvt_pk_bf16_f32 v48, v55, s0
	s_waitcnt lgkmcnt(0)
	v_pk_mul_f32 v[54:55], v[18:19], v[54:55]
	ds_write_b16 v107, v48 offset:55296
	v_pk_mul_f32 v[18:19], v[50:51], v[52:53]
	v_add_u32_e32 v89, 0x190, v86
	v_cvt_pk_bf16_f32 v48, v18, s0
	v_pk_mul_f32 v[50:51], v[20:21], v[18:19]
	ds_write_b16 v108, v48 offset:55296
	v_cvt_pk_bf16_f32 v48, v19, s0
	v_cvt_pk_bf16_f32 v18, v98, v99
	v_cvt_pk_bf16_f32 v19, v104, v105
	v_cvt_pk_bf16_f32 v20, v54, v55
	v_cvt_pk_bf16_f32 v21, v50, v51
	ds_write_b16 v109, v48 offset:55296
	ds_write_b128 v49, v[18:21] offset:18432
	v_ashrrev_i32_e32 v18, 3, v17
	v_and_b32_e32 v18, -16, v18
	v_or_b32_e32 v98, v18, v58
	v_mul_lo_u32 v19, v98, s35
	v_add_u32_e32 v20, 0, v19
	v_lshlrev_b32_e32 v19, 2, v62
	v_add_u32_e32 v101, s34, v19
	s_add_i32 s34, 0, 0x16320
	v_and_b32_e32 v17, 48, v17
	v_add_u32_e32 v102, s34, v19
	v_add_u32_e32 v103, s9, v19
	v_mov_b32_e32 v19, 0x6590
	v_add_u32_e32 v99, v20, v17
	v_add_u32_e32 v100, 0, v17
	v_lshlrev_b32_e32 v17, 2, v116
	v_cndmask_b32_e64 v105, v19, 0, s[46:47]
	v_lshlrev_b32_e32 v19, 3, v116
	v_lshlrev_b32_e32 v18, 1, v18
	v_add3_u32 v106, 0, v19, v18
	v_or_b32_e32 v18, v115, v58
	v_or_b32_e32 v48, v115, v17
	v_mul_u32_u24_e32 v107, 0x90, v18
	v_or_b32_e32 v18, 3, v48
	v_or_b32_e32 v19, 2, v48
	v_cmp_gt_i32_e64 s[62:63], v18, v98
	v_or_b32_e32 v18, 16, v115
	v_cmp_gt_i32_e64 s[64:65], v19, v98
	v_or_b32_e32 v19, v18, v58
	v_or_b32_e32 v17, v18, v17
	v_mul_u32_u24_e32 v108, 0x90, v19
	v_or_b32_e32 v18, 3, v17
	v_or_b32_e32 v19, 2, v17
	v_cmp_gt_i32_e64 s[70:71], v18, v98
	v_cmp_gt_i32_e64 s[72:73], v19, v98
	v_lshl_add_u64 v[18:19], s[12:13], 0, v[168:169]
	v_lshl_add_u64 v[50:51], v[18:19], 0, v[22:23]
	v_lshl_add_u64 v[18:19], s[12:13], 0, v[24:25]
	v_lshl_add_u64 v[52:53], v[18:19], 0, v[26:27]
	v_lshl_add_u64 v[18:19], s[12:13], 0, v[28:29]
	v_lshl_add_u64 v[54:55], v[18:19], 0, v[30:31]
	v_cndmask_b32_e64 v18, v118, v119, s[74:75]
	s_add_u32 s9, s14, s84
	v_or_b32_e32 v18, s76, v18
	v_mov_b32_e32 v19, s77
	s_addc_u32 s34, s15, 0
	v_cndmask_b32_e32 v18, v18, v19, vcc
	s_add_u32 s76, s9, s8
	v_lshlrev_b32_e32 v168, 1, v18
	s_addc_u32 s77, s34, 0
	s_lshl_b32 s8, s31, 1
	v_lshlrev_b32_e32 v21, 1, v48
	v_cmp_gt_i32_e64 s[66:67], v17, v98
	v_cmp_lt_i32_e64 s[68:69], v17, v98
	v_lshlrev_b32_e32 v17, 1, v17
	v_lshl_add_u64 v[18:19], s[12:13], 0, v[168:169]
	s_add_u32 s8, s16, s8
	v_add_u32_e32 v90, 0x320, v86
	v_add_u32_e32 v91, 0x4b0, v86
	v_add_u32_e32 v92, 0x640, v86
	v_add_u32_e32 v93, 0x7d0, v86
	v_add_u32_e32 v94, 0x960, v86
	v_cndmask_b32_e64 v104, 64, -1, s[46:47]
	v_cmp_eq_u32_e64 s[46:47], 0, v58
	v_cmp_lt_u32_e64 s[48:49], 1, v58
	v_cmp_lt_u32_e64 s[50:51], 3, v58
	v_cmp_lt_u32_e64 s[52:53], 7, v58
	v_cmp_eq_u32_e64 s[54:55], 0, v60
	v_cmp_lt_u32_e64 s[56:57], 31, v62
	v_cmp_gt_i32_e64 s[58:59], v48, v98
	v_cmp_lt_i32_e64 s[60:61], v48, v98
	v_lshl_add_u64 v[56:57], v[18:19], 0, v[56:57]
	v_mov_b32_e32 v47, v46
	v_mov_b32_e32 v58, v43
	v_mov_b32_e32 v59, v42
	s_addc_u32 s9, s17, 0
	v_lshlrev_b32_e32 v168, 1, v48
	v_add_u32_e32 v109, v20, v21
	v_add_u32_e32 v110, v20, v17
	s_mov_b32 s35, 0
	v_mov_b32_e32 v17, v16
	v_mov_b32_e32 v18, v16
	v_mov_b32_e32 v19, v16
	v_mov_b32_e32 v20, v16
	v_mov_b32_e32 v21, v16
	v_mov_b32_e32 v22, v16
	v_mov_b32_e32 v23, v16
	s_waitcnt lgkmcnt(0)
	s_barrier
	v_lshrrev_b32_e32 v196, 6, v171
	v_lshlrev_b32_e32 v196, 1, v196
	v_bfe_u32 v197, v171, 3, 1
	v_add_u32_e32 v196, v196, v197
	v_lshlrev_b32_e32 v196, 2, v196
	v_bfe_u32 v197, v171, 4, 2
	v_lshlrev_b32_e32 v197, 3, v197
	v_and_b32_e32 v202, 7, v171
	v_add_u32_e32 v197, v197, v202
	v_mul_u32_u24_e32 v198, 0x190, v196
	v_lshl_add_u32 v198, v197, 2, v198
	v_add_u32_e32 v198, 0xfc00, v198
	v_mul_u32_u24_e32 v199, 0x90, v196
	v_lshl_add_u32 v199, v197, 2, v199
	v_mul_u32_u24_e32 v200, 0x120, v197
	v_lshl_add_u32 v200, v196, 1, v200
	v_lshlrev_b32_e32 v201, 2, v196
	v_add_u32_e32 v201, 0x16520, v201
	v_lshlrev_b32_e32 v202, 3, v197
	v_add_u32_e32 v203, 4, v202
	ds_bpermute_b32 v172, v202, v32
	ds_bpermute_b32 v173, v203, v32
	ds_bpermute_b32 v174, v202, v34
	ds_bpermute_b32 v175, v203, v34
	ds_bpermute_b32 v176, v202, v36
	ds_bpermute_b32 v177, v203, v36
	ds_bpermute_b32 v178, v202, v38
	ds_bpermute_b32 v179, v203, v38
	ds_bpermute_b32 v180, v202, v40
	ds_bpermute_b32 v181, v203, v40
	ds_bpermute_b32 v182, v202, v43
	ds_bpermute_b32 v183, v203, v43
	ds_bpermute_b32 v184, v202, v42
	ds_bpermute_b32 v185, v203, v42
	ds_bpermute_b32 v186, v202, v44
	ds_bpermute_b32 v187, v203, v44
	ds_bpermute_b32 v188, v202, v63
	ds_bpermute_b32 v189, v203, v63
	ds_bpermute_b32 v190, v202, v64
	ds_bpermute_b32 v191, v203, v64
	ds_bpermute_b32 v192, v202, v65
	ds_bpermute_b32 v193, v203, v65
	ds_bpermute_b32 v194, v202, v66
	ds_bpermute_b32 v195, v203, v66
	v_bfe_u32 v250, v171, 2, 1
	v_mul_u32_u24_e32 v250, 0x90, v250
	s_waitcnt lgkmcnt(0)
	s_branch .LBB0_443
.LBB0_442:
	s_mul_i32 s16, s34, 0x18920
	s_xor_b32 s74, s34, 1
	s_mul_i32 s17, s74, 0x6b00
	s_add_i32 s34, s17, 0
	ds_read_b128 v[224:227], v99 offset:36864
	ds_read_b128 v[228:231], v99 offset:36928
	v_add_u32_e32 v222, s16, v100
	v_add_u32_e32 v223, v222, v107
	ds_read_b128 v[232:235], v223 offset:18432
	ds_read_b128 v[236:239], v223 offset:18496
	ds_read_b64 v[240:241], v109 offset:55296
	v_add_u32_e32 v242, v222, v108
	ds_read_b128 v[244:247], v242 offset:18432
	v_mul_f32_e32 v61, 0x3fb8aa3b, v61
	v_exp_f32_e32 v112, v61
	v_ashrrev_i32_e32 v61, 31, v60
	v_lshlrev_b64 v[60:61], 11, v[60:61]
	v_lshl_add_u64 v[124:125], s[8:9], 0, v[60:61]
	v_add_u32_e32 v60, s16, v100
	v_add_u32_e32 v61, v60, v107
	v_pk_mul_f32 v[26:27], v[112:113], v[26:27] op_sel_hi:[0,1]
	v_pk_mul_f32 v[24:25], v[112:113], v[24:25] op_sel_hi:[0,1]
	v_pk_mul_f32 v[30:31], v[112:113], v[30:31] op_sel_hi:[0,1]
	v_pk_mul_f32 v[28:29], v[112:113], v[28:29] op_sel_hi:[0,1]
	s_waitcnt lgkmcnt(2)
	v_mfma_f32_16x16x32_bf16 v[24:27], v[232:235], v[224:227], v[24:27]
	v_add_u32_e32 v60, v60, v108
	v_mfma_f32_16x16x32_bf16 v[24:27], v[236:239], v[228:231], v[24:27]
	v_add3_u32 v111, s34, v82, v83
	v_add_u32_e32 v128, 0xfc00, v111
	s_waitcnt lgkmcnt(1)
	v_lshlrev_b32_e32 v122, 16, v240
	v_and_b32_e32 v123, 0xffff0000, v240
	v_lshlrev_b32_e32 v120, 16, v241
	v_and_b32_e32 v121, 0xffff0000, v241
	s_nop 0
	v_pk_fma_f32 v[24:25], v[46:47], v[122:123], v[24:25]
	v_pk_fma_f32 v[26:27], v[46:47], v[120:121], v[26:27]
	v_cvt_pk_bf16_f32 v24, v24, v25
	v_cvt_pk_bf16_f32 v25, v26, v27
	v_lshl_add_u64 v[120:121], v[124:125], 0, v[168:169]
	global_store_dwordx2 v[120:121], v[24:25], off offset:512
	s_waitcnt lgkmcnt(0)
	v_mfma_f32_16x16x32_bf16 v[24:27], v[244:247], v[224:227], v[28:31]
	s_nop 2
	ds_read_b128 v[28:31], v60 offset:18496
	v_add_u32_e32 v124, s17, v85
	v_add3_u32 v112, s34, v86, v83
	s_waitcnt lgkmcnt(0)
	v_mfma_f32_16x16x32_bf16 v[24:27], v[28:31], v[228:231], v[24:27]
	ds_read_b64 v[28:29], v110 offset:55296
	v_add3_u32 v113, s34, v89, v83
	s_mul_i32 s74, s74, 0x18920
	s_add_i32 s29, s29, 64
	s_cmpk_eq_i32 s31, 0x84
	s_waitcnt lgkmcnt(0)
	v_lshlrev_b32_e32 v30, 16, v28
	v_and_b32_e32 v31, 0xffff0000, v28
	v_lshlrev_b32_e32 v28, 16, v29
	v_and_b32_e32 v29, 0xffff0000, v29
	v_pk_fma_f32 v[24:25], v[46:47], v[30:31], v[24:25]
	v_pk_fma_f32 v[26:27], v[46:47], v[28:29], v[26:27]
	v_cvt_pk_bf16_f32 v24, v24, v25
	v_cvt_pk_bf16_f32 v25, v26, v27
	global_store_dwordx2 v[120:121], v[24:25], off offset:544
	v_add_u32_e32 v122, s17, v198
	v_add_u32_e32 v124, s17, v201
	v_add_u32_e32 v123, s74, v200
	v_mov_b32_e32 v154, 0xbfb8aa3b
	ds_read_b32 v131, v122 offset:128
	ds_read_b32 v133, v122 offset:528
	ds_read_b32 v135, v122 offset:928
	ds_read_b32 v137, v122 offset:1328
	ds_read_b32 v139, v122 offset:1728
	ds_read_b32 v141, v122 offset:2128
	ds_read_b128 v[156:159], v124
	ds_read_b32 v143, v122 offset:256
	ds_read_b32 v145, v122 offset:656
	ds_read_b32 v147, v122 offset:1056
	ds_read_b32 v149, v122 offset:1456
	ds_read_b32 v151, v122 offset:1856
	ds_read_b32 v153, v122 offset:2256
	s_waitcnt lgkmcnt(10)
	v_lshlrev_b32_e32 v130, 16, v131
	v_and_b32_e32 v131, 0xffff0000, v131
	v_lshlrev_b32_e32 v132, 16, v133
	v_and_b32_e32 v133, 0xffff0000, v133
	v_lshlrev_b32_e32 v134, 16, v135
	v_and_b32_e32 v135, 0xffff0000, v135
	s_waitcnt lgkmcnt(7)
	v_lshlrev_b32_e32 v136, 16, v137
	v_and_b32_e32 v137, 0xffff0000, v137
	v_lshlrev_b32_e32 v138, 16, v139
	v_and_b32_e32 v139, 0xffff0000, v139
	v_lshlrev_b32_e32 v140, 16, v141
	v_and_b32_e32 v141, 0xffff0000, v141
	v_pk_mul_f32 v[160:161], v[180:181], v[130:131]
	v_pk_mul_f32 v[162:163], v[180:181], v[132:133]
	v_pk_mul_f32 v[164:165], v[180:181], v[134:135]
	v_pk_mul_f32 v[166:167], v[180:181], v[136:137]
	v_pk_fma_f32 v[160:161], v[182:183], v[132:133], v[160:161]
	v_pk_fma_f32 v[162:163], v[182:183], v[134:135], v[162:163]
	v_pk_fma_f32 v[164:165], v[182:183], v[136:137], v[164:165]
	v_pk_fma_f32 v[166:167], v[182:183], v[138:139], v[166:167]
	v_pk_fma_f32 v[160:161], v[184:185], v[134:135], v[160:161]
	v_pk_fma_f32 v[162:163], v[184:185], v[136:137], v[162:163]
	v_pk_fma_f32 v[164:165], v[184:185], v[138:139], v[164:165]
	v_pk_fma_f32 v[166:167], v[184:185], v[140:141], v[166:167]
	v_pk_add_f32 v[160:161], v[186:187], v[160:161]
	v_pk_add_f32 v[162:163], v[186:187], v[162:163]
	v_pk_add_f32 v[164:165], v[186:187], v[164:165]
	v_pk_add_f32 v[166:167], v[186:187], v[166:167]
	v_pk_mul_f32 v[24:25], v[160:161], v[154:155] op_sel_hi:[1,0]
	v_pk_mul_f32 v[26:27], v[162:163], v[154:155] op_sel_hi:[1,0]
	v_pk_mul_f32 v[28:29], v[164:165], v[154:155] op_sel_hi:[1,0]
	v_pk_mul_f32 v[30:31], v[166:167], v[154:155] op_sel_hi:[1,0]
	v_exp_f32_e32 v24, v24
	v_exp_f32_e32 v26, v26
	v_exp_f32_e32 v28, v28
	v_exp_f32_e32 v30, v30
	v_exp_f32_e32 v25, v25
	v_exp_f32_e32 v27, v27
	v_exp_f32_e32 v29, v29
	v_exp_f32_e32 v31, v31
	v_pk_add_f32 v[24:25], v[24:25], 1.0 op_sel_hi:[1,0]
	v_pk_add_f32 v[26:27], v[26:27], 1.0 op_sel_hi:[1,0]
	v_pk_add_f32 v[28:29], v[28:29], 1.0 op_sel_hi:[1,0]
	v_pk_add_f32 v[30:31], v[30:31], 1.0 op_sel_hi:[1,0]
	v_rcp_f32_e32 v24, v24
	v_rcp_f32_e32 v26, v26
	v_rcp_f32_e32 v28, v28
	v_rcp_f32_e32 v30, v30
	v_rcp_f32_e32 v25, v25
	v_rcp_f32_e32 v27, v27
	v_rcp_f32_e32 v29, v29
	v_rcp_f32_e32 v31, v31
	v_pk_mul_f32 v[160:161], v[160:161], v[24:25]
	v_pk_mul_f32 v[162:163], v[162:163], v[26:27]
	v_pk_mul_f32 v[164:165], v[164:165], v[28:29]
	v_pk_mul_f32 v[166:167], v[166:167], v[30:31]
	v_cvt_pk_bf16_f32 v24, v160, v161
	v_cvt_pk_bf16_f32 v26, v162, v163
	v_cvt_pk_bf16_f32 v28, v164, v165
	v_cvt_pk_bf16_f32 v30, v166, v167
	ds_write_b32 v199, v24 offset:9216
	ds_write_b32 v199, v26 offset:9360
	ds_write_b32 v199, v28 offset:9504
	ds_write_b32 v199, v30 offset:9648
	s_waitcnt lgkmcnt(10)
	v_pk_mul_f32 v[112:113], v[160:161], v[156:157] op_sel_hi:[1,0]
	v_pk_mul_f32 v[114:115], v[162:163], v[156:157] op_sel:[0,1]
	v_pk_mul_f32 v[116:117], v[164:165], v[158:159] op_sel_hi:[1,0]
	v_pk_mul_f32 v[118:119], v[166:167], v[158:159] op_sel:[0,1]
	v_cvt_pk_bf16_f32 v24, v112, v114
	v_cvt_pk_bf16_f32 v25, v116, v118
	v_cvt_pk_bf16_f32 v26, v113, v115
	v_cvt_pk_bf16_f32 v27, v117, v119
	v_and_b32_e32 v28, 4, v171
	v_cmp_ne_u32_e32 vcc, 0, v28
	v_add_u32_e32 v248, v123, v250
	v_sub_u32_e32 v249, v123, v250
	v_cndmask_b32_e32 v28, v24, v26, vcc
	v_cndmask_b32_e32 v29, v25, v27, vcc
	v_cndmask_b32_e32 v30, v26, v24, vcc
	v_cndmask_b32_e32 v31, v27, v25, vcc
	ds_write_b64 v248, v[28:29] offset:27648
	ds_write_b64 v249, v[30:31] offset:27792
	s_waitcnt lgkmcnt(9)
	v_lshlrev_b32_e32 v142, 16, v143
	v_and_b32_e32 v143, 0xffff0000, v143
	v_lshlrev_b32_e32 v144, 16, v145
	v_and_b32_e32 v145, 0xffff0000, v145
	v_lshlrev_b32_e32 v146, 16, v147
	v_and_b32_e32 v147, 0xffff0000, v147
	s_waitcnt lgkmcnt(6)
	v_lshlrev_b32_e32 v148, 16, v149
	v_and_b32_e32 v149, 0xffff0000, v149
	v_lshlrev_b32_e32 v150, 16, v151
	v_and_b32_e32 v151, 0xffff0000, v151
	v_lshlrev_b32_e32 v152, 16, v153
	v_and_b32_e32 v153, 0xffff0000, v153
	v_pk_mul_f32 v[160:161], v[188:189], v[142:143]
	v_pk_mul_f32 v[162:163], v[188:189], v[144:145]
	v_pk_mul_f32 v[164:165], v[188:189], v[146:147]
	v_pk_mul_f32 v[166:167], v[188:189], v[148:149]
	v_pk_fma_f32 v[160:161], v[190:191], v[144:145], v[160:161]
	v_pk_fma_f32 v[162:163], v[190:191], v[146:147], v[162:163]
	v_pk_fma_f32 v[164:165], v[190:191], v[148:149], v[164:165]
	v_pk_fma_f32 v[166:167], v[190:191], v[150:151], v[166:167]
	v_pk_fma_f32 v[160:161], v[192:193], v[146:147], v[160:161]
	v_pk_fma_f32 v[162:163], v[192:193], v[148:149], v[162:163]
	v_pk_fma_f32 v[164:165], v[192:193], v[150:151], v[164:165]
	v_pk_fma_f32 v[166:167], v[192:193], v[152:153], v[166:167]
	v_pk_add_f32 v[160:161], v[194:195], v[160:161]
	v_pk_add_f32 v[162:163], v[194:195], v[162:163]
	v_pk_add_f32 v[164:165], v[194:195], v[164:165]
	v_pk_add_f32 v[166:167], v[194:195], v[166:167]
	v_pk_mul_f32 v[24:25], v[160:161], v[154:155] op_sel_hi:[1,0]
	v_pk_mul_f32 v[26:27], v[162:163], v[154:155] op_sel_hi:[1,0]
	v_pk_mul_f32 v[28:29], v[164:165], v[154:155] op_sel_hi:[1,0]
	v_pk_mul_f32 v[30:31], v[166:167], v[154:155] op_sel_hi:[1,0]
	v_exp_f32_e32 v24, v24
	v_exp_f32_e32 v26, v26
	v_exp_f32_e32 v28, v28
	v_exp_f32_e32 v30, v30
	v_exp_f32_e32 v25, v25
	v_exp_f32_e32 v27, v27
	v_exp_f32_e32 v29, v29
	v_exp_f32_e32 v31, v31
	v_pk_add_f32 v[24:25], v[24:25], 1.0 op_sel_hi:[1,0]
	v_pk_add_f32 v[26:27], v[26:27], 1.0 op_sel_hi:[1,0]
	v_pk_add_f32 v[28:29], v[28:29], 1.0 op_sel_hi:[1,0]
	v_pk_add_f32 v[30:31], v[30:31], 1.0 op_sel_hi:[1,0]
	v_rcp_f32_e32 v24, v24
	v_rcp_f32_e32 v26, v26
	v_rcp_f32_e32 v28, v28
	v_rcp_f32_e32 v30, v30
	v_rcp_f32_e32 v25, v25
	v_rcp_f32_e32 v27, v27
	v_rcp_f32_e32 v29, v29
	v_rcp_f32_e32 v31, v31
	v_pk_mul_f32 v[160:161], v[160:161], v[24:25]
	v_pk_mul_f32 v[162:163], v[162:163], v[26:27]
	v_pk_mul_f32 v[164:165], v[164:165], v[28:29]
	v_pk_mul_f32 v[166:167], v[166:167], v[30:31]
	v_cvt_pk_bf16_f32 v24, v160, v161
	v_cvt_pk_bf16_f32 v26, v162, v163
	v_cvt_pk_bf16_f32 v28, v164, v165
	v_cvt_pk_bf16_f32 v30, v166, v167
	ds_write_b32 v199, v24 offset:0
	ds_write_b32 v199, v26 offset:144
	ds_write_b32 v199, v28 offset:288
	ds_write_b32 v199, v30 offset:432
	s_mov_b32 s35, s31
	v_add_u32_e32 v121, s16, v99
	v_mov_b32_e32 v24, s84
	s_waitcnt lgkmcnt(0)
	s_barrier
	ds_read_b32 v222, v24 offset:252
	ds_read_b128 v[224:227], v121 offset:27648
	ds_read_b128 v[228:231], v61 offset:18432
	ds_read_b128 v[232:235], v121 offset:27712
	ds_read_b128 v[236:239], v61 offset:18496
	ds_read_b128 v[240:243], v121 offset:27648
	ds_read_b128 v[244:247], v60 offset:18432
	s_waitcnt lgkmcnt(6)
	v_mul_f32_e32 v24, 0x3fb8aa3b, v222
	v_exp_f32_e32 v120, v24
	s_nop 0
	v_pk_mul_f32 v[18:19], v[18:19], v[120:121] op_sel_hi:[1,0]
	v_pk_mul_f32 v[16:17], v[16:17], v[120:121] op_sel_hi:[1,0]
	v_pk_mul_f32 v[22:23], v[22:23], v[120:121] op_sel_hi:[1,0]
	v_pk_mul_f32 v[20:21], v[20:21], v[120:121] op_sel_hi:[1,0]
	s_waitcnt lgkmcnt(2)
	v_mfma_f32_16x16x32_bf16 v[16:19], v[224:227], v[228:231], v[16:19]
	v_mfma_f32_16x16x32_bf16 v[16:19], v[232:235], v[236:239], v[16:19]
	v_add_u32_e32 v26, v106, v107
	s_nop 6
	v_cvt_pk_bf16_f32 v24, v16, v17
	v_cvt_pk_bf16_f32 v25, v18, v19
	ds_write_b64 v26, v[24:25] offset:46080
	s_waitcnt lgkmcnt(1)
	v_mfma_f32_16x16x32_bf16 v[20:23], v[240:243], v[244:247], v[20:23]
	ds_read_b128 v[24:27], v121 offset:27712
	ds_read_b128 v[28:31], v60 offset:18496
	s_waitcnt lgkmcnt(0)
	v_mfma_f32_16x16x32_bf16 v[20:23], v[24:27], v[28:31], v[20:23]
	v_add_u32_e32 v26, v106, v108
	s_nop 6
	v_cvt_pk_bf16_f32 v24, v20, v21
	v_cvt_pk_bf16_f32 v25, v22, v23
	ds_write_b64 v26, v[24:25] offset:46080
	v_add_u32_e32 v122, s17, v198
	v_add_u32_e32 v124, s17, v201
	v_add_u32_e32 v124, 0xffffff00, v124
	v_add_u32_e32 v123, s74, v200
	v_mov_b32_e32 v154, 0xbfb8aa3b
	ds_read_b32 v131, v122 offset:0
	ds_read_b32 v133, v122 offset:400
	ds_read_b32 v135, v122 offset:800
	ds_read_b32 v137, v122 offset:1200
	ds_read_b32 v139, v122 offset:1600
	ds_read_b32 v141, v122 offset:2000
	ds_read_b128 v[156:159], v124
	s_waitcnt lgkmcnt(4)
	v_lshlrev_b32_e32 v130, 16, v131
	v_and_b32_e32 v131, 0xffff0000, v131
	v_lshlrev_b32_e32 v132, 16, v133
	v_and_b32_e32 v133, 0xffff0000, v133
	v_lshlrev_b32_e32 v134, 16, v135
	v_and_b32_e32 v135, 0xffff0000, v135
	s_waitcnt lgkmcnt(1)
	v_lshlrev_b32_e32 v136, 16, v137
	v_and_b32_e32 v137, 0xffff0000, v137
	v_lshlrev_b32_e32 v138, 16, v139
	v_and_b32_e32 v139, 0xffff0000, v139
	v_lshlrev_b32_e32 v140, 16, v141
	v_and_b32_e32 v141, 0xffff0000, v141
	v_pk_mul_f32 v[160:161], v[172:173], v[130:131]
	v_pk_mul_f32 v[162:163], v[172:173], v[132:133]
	v_pk_mul_f32 v[164:165], v[172:173], v[134:135]
	v_pk_mul_f32 v[166:167], v[172:173], v[136:137]
	v_pk_fma_f32 v[160:161], v[174:175], v[132:133], v[160:161]
	v_pk_fma_f32 v[162:163], v[174:175], v[134:135], v[162:163]
	v_pk_fma_f32 v[164:165], v[174:175], v[136:137], v[164:165]
	v_pk_fma_f32 v[166:167], v[174:175], v[138:139], v[166:167]
	v_pk_fma_f32 v[160:161], v[176:177], v[134:135], v[160:161]
	v_pk_fma_f32 v[162:163], v[176:177], v[136:137], v[162:163]
	v_pk_fma_f32 v[164:165], v[176:177], v[138:139], v[164:165]
	v_pk_fma_f32 v[166:167], v[176:177], v[140:141], v[166:167]
	v_pk_add_f32 v[160:161], v[178:179], v[160:161]
	v_pk_add_f32 v[162:163], v[178:179], v[162:163]
	v_pk_add_f32 v[164:165], v[178:179], v[164:165]
	v_pk_add_f32 v[166:167], v[178:179], v[166:167]
	v_pk_mul_f32 v[24:25], v[160:161], v[154:155] op_sel_hi:[1,0]
	v_pk_mul_f32 v[26:27], v[162:163], v[154:155] op_sel_hi:[1,0]
	v_pk_mul_f32 v[28:29], v[164:165], v[154:155] op_sel_hi:[1,0]
	v_pk_mul_f32 v[30:31], v[166:167], v[154:155] op_sel_hi:[1,0]
	v_exp_f32_e32 v24, v24
	v_exp_f32_e32 v26, v26
	v_exp_f32_e32 v28, v28
	v_exp_f32_e32 v30, v30
	v_exp_f32_e32 v25, v25
	v_exp_f32_e32 v27, v27
	v_exp_f32_e32 v29, v29
	v_exp_f32_e32 v31, v31
	v_pk_add_f32 v[24:25], v[24:25], 1.0 op_sel_hi:[1,0]
	v_pk_add_f32 v[26:27], v[26:27], 1.0 op_sel_hi:[1,0]
	v_pk_add_f32 v[28:29], v[28:29], 1.0 op_sel_hi:[1,0]
	v_pk_add_f32 v[30:31], v[30:31], 1.0 op_sel_hi:[1,0]
	v_rcp_f32_e32 v24, v24
	v_rcp_f32_e32 v26, v26
	v_rcp_f32_e32 v28, v28
	v_rcp_f32_e32 v30, v30
	v_rcp_f32_e32 v25, v25
	v_rcp_f32_e32 v27, v27
	v_rcp_f32_e32 v29, v29
	v_rcp_f32_e32 v31, v31
	v_pk_mul_f32 v[160:161], v[160:161], v[24:25]
	v_pk_mul_f32 v[162:163], v[162:163], v[26:27]
	v_pk_mul_f32 v[164:165], v[164:165], v[28:29]
	v_pk_mul_f32 v[166:167], v[166:167], v[30:31]
	v_cvt_pk_bf16_f32 v24, v160, v161
	v_cvt_pk_bf16_f32 v26, v162, v163
	v_cvt_pk_bf16_f32 v28, v164, v165
	v_cvt_pk_bf16_f32 v30, v166, v167
	ds_write_b32 v199, v24 offset:55296
	ds_write_b32 v199, v26 offset:55440
	ds_write_b32 v199, v28 offset:55584
	ds_write_b32 v199, v30 offset:55728
	s_waitcnt lgkmcnt(4)
	v_pk_mul_f32 v[112:113], v[160:161], v[156:157] op_sel_hi:[1,0]
	v_pk_mul_f32 v[114:115], v[162:163], v[156:157] op_sel:[0,1]
	v_pk_mul_f32 v[116:117], v[164:165], v[158:159] op_sel_hi:[1,0]
	v_pk_mul_f32 v[118:119], v[166:167], v[158:159] op_sel:[0,1]
	v_cvt_pk_bf16_f32 v24, v112, v114
	v_cvt_pk_bf16_f32 v25, v116, v118
	v_cvt_pk_bf16_f32 v26, v113, v115
	v_cvt_pk_bf16_f32 v27, v117, v119
	v_and_b32_e32 v28, 4, v171
	v_cmp_ne_u32_e32 vcc, 0, v28
	v_add_u32_e32 v248, v123, v250
	v_sub_u32_e32 v249, v123, v250
	v_cndmask_b32_e32 v28, v24, v26, vcc
	v_cndmask_b32_e32 v29, v25, v27, vcc
	v_cndmask_b32_e32 v30, v26, v24, vcc
	v_cndmask_b32_e32 v31, v27, v25, vcc
	ds_write_b64 v248, v[28:29] offset:18432
	ds_write_b64 v249, v[30:31] offset:18576
	s_waitcnt lgkmcnt(0)
	s_barrier
	s_cbranch_scc1 .LBB0_474
